# P4: the workgroups without a split unit stream x through the memory-side cache first (1 MB each) so the residual reads of the tile epilogues are warm
# baseline (speedup 1.0000x reference)
.LBB0_1464:
	s_andn2_b64 vcc, exec, s[8:9]
	s_cbranch_vccnz .LBB0_1505
	s_cmp_lg_u32 s96, 0x100
	s_cbranch_scc1 .Lxpf_skip
	s_cmpk_lt_i32 s97, 0x80
	s_cbranch_scc1 .Lxpf_skip
	s_sub_i32 s8, s97, 0x80
	s_lshl_b32 s8, s8, 20
	s_add_u32 s8, s56, s8
	s_addc_u32 s9, s57, 0
	v_lshlrev_b32_e32 v2, 4, v0
	s_movk_i32 s5, 0x20
	v_add_u32_e32 v3, 0x2000, v2
	v_add_u32_e32 v8, 0x4000, v2
	v_add_u32_e32 v9, 0x6000, v2
.Lxpf_loop:
	global_load_dwordx4 v[4:7], v2, s[8:9]
	global_load_dwordx4 v[4:7], v3, s[8:9]
	global_load_dwordx4 v[4:7], v8, s[8:9]
	global_load_dwordx4 v[4:7], v9, s[8:9]
	s_add_u32 s8, s8, 0x8000
	s_addc_u32 s9, s9, 0
	s_sub_i32 s5, s5, 1
	s_cmp_lg_u32 s5, 0
	s_cbranch_scc1 .Lxpf_loop
	s_waitcnt vmcnt(0)
.Lxpf_skip:
	s_add_u32 s21, s76, 0x2c800000
	s_addc_u32 s37, s77, 0
	s_add_u32 s54, s76, 0x5600000
	v_lshlrev_b32_e32 v2, 4, v0
	s_addc_u32 s60, s77, 0
	v_and_b32_e32 v3, 32, v0
	v_or_b32_e32 v14, 0x2000, v2
	s_lshr_b32 s13, s14, 6
	s_ashr_i32 s39, s38, 31
	s_lshr_b32 s12, s14, 8
	v_bfe_u32 v13, v0, 2, 4
	v_bitop3_b32 v11, v2, v3, 48 bitop3:0x6c
	v_lshrrev_b32_e32 v2, 7, v14
	s_movk_i32 s5, 0x70
	s_lshl_b32 s61, s13, 10
	s_lshl_b64 s[8:9], s[38:39], 20
	v_and_or_b32 v2, v2, s5, v13
	s_add_u32 s5, s21, s8
	s_addc_u32 s10, s37, s9
	s_ashr_i32 s47, s46, 31
	s_lshl_b64 s[8:9], s[46:47], 20
	s_add_u32 s8, s54, s8
	s_addc_u32 s9, s60, s9
	v_and_b32_e32 v12, 64, v0
	v_lshrrev_b32_e32 v4, 3, v0
	s_add_u32 s50, s8, s6
	v_or_b32_e32 v3, v11, v12
	v_and_or_b32 v4, v4, 48, v13
	s_addc_u32 s51, s9, s7
	s_add_i32 s62, s61, 0
	v_lshl_or_b32 v162, v4, 12, v3
	s_add_i32 m0, s62, 0x10000
	v_lshl_or_b32 v164, v2, 12, v3
	global_load_lds_dwordx4 v162, s[50:51]
	s_add_i32 m0, s62, 0x12000
	s_add_u32 s8, s50, 0x80000
	global_load_lds_dwordx4 v164, s[50:51]
	s_addc_u32 s9, s51, 0
	s_add_i32 m0, s62, 0x14000
	v_mov_b32_e32 v163, 0
	global_load_lds_dwordx4 v162, s[8:9]
	s_add_i32 m0, s62, 0x16000
	s_add_u32 s48, s5, s6
	s_addc_u32 s49, s10, s7
	s_add_i32 s63, s62, 0x2000
	global_load_lds_dwordx4 v164, s[8:9]
	s_mov_b32 m0, s62
	s_add_u32 s6, s48, 0x80000
	global_load_lds_dwordx4 v162, s[48:49]
	s_mov_b32 m0, s63
	s_addc_u32 s7, s49, 0
	s_add_i32 s64, s62, 0x4000
	global_load_lds_dwordx4 v164, s[48:49]
	s_mov_b32 m0, s64
	s_add_i32 s65, s62, 0x6000
	global_load_lds_dwordx4 v162, s[6:7]
	s_mov_b32 m0, s65
	v_mov_b32_e32 v165, v163
	global_load_lds_dwordx4 v164, s[6:7]
	s_cmp_eq_u32 s12, 1
	s_mov_b32 s5, 0
	v_lshl_add_u64 v[8:9], s[50:51], 0, v[162:163]
	v_lshl_add_u64 v[6:7], s[50:51], 0, v[164:165]
	v_lshl_add_u64 v[2:3], s[48:49], 0, v[162:163]
	s_cselect_b64 s[6:7], -1, 0
	s_cmp_lg_u32 s12, 1
	v_lshl_add_u64 v[4:5], s[48:49], 0, v[164:165]
	s_cbranch_scc1 .LBB0_1467
	s_barrier
